# baseline (speedup 1.0000x reference)
; __device__ __forceinline__ float bf2f(u16 h) { return __uint_as_float(((unsigned)h) << 16); }
; #define LAUNDER_IDS int tid = hw_tid(); asm volatile("" : "+v"(tid)); int bid = blockIdx.x; asm volatile("" : "+s"(bid)); const int gdim = gridDim.x
; __device__ __forceinline__ void phase_final(PP p, const int g_wid) {
;   LAUNDER_IDS; const int gtid = bid * 512 + tid, gsz = gdim * 512;
;   const int wave = gtid >> 6, nw = gsz >> 6, lane = tid & 63;
;   for (int r = wave; r < 49152; r += nw) {
;     int hrw;
;     if (r < 16384) { int s = r >> 11; hrw = s * 2064 + 16 + (r & 2047); }
;     else { int r2 = r - 16384; int s = r2 >> 14; hrw = 16512 + s * 16400 + 16 + (r2 & 16383); }
;     const u16* hb = p->hb + (long)hrw * 1024;
;     float* orow = p->out + (long)r * 1024;
;     float4 v[4];
;     float sq = 0.f;
; #pragma unroll
;     for (int k = 0; k < 4; ++k) {
;       const u16x4 h4 = *reinterpret_cast<const u16x4*>(hb + k * 256 + lane * 4);
;       v[k] = make_float4(bf2f(h4[0]), bf2f(h4[1]), bf2f(h4[2]), bf2f(h4[3]));
;       sq += v[k].x * v[k].x + v[k].y * v[k].y + v[k].z * v[k].z + v[k].w * v[k].w;
;     }
; #pragma unroll
;     for (int o = 1; o < 64; o <<= 1) sq += __shfl_xor(sq, o);
;     float rs = rsqrtf(sq * (1.f / 1024.f) + 1e-6f);
; #pragma unroll
;     for (int k = 0; k < 4; ++k) {
;       float4 g = *reinterpret_cast<const float4*>(p->final_norm + k * 256 + lane * 4);
;       float4 o = make_float4(v[k].x * rs * g.x, v[k].y * rs * g.y, v[k].z * rs * g.z, v[k].w * rs * g.w);
;       *reinterpret_cast<float4*>(orow + k * 256 + lane * 4) = o;
;     }
;   }
.LBB0_654:
	s_or_b64 exec, exec, s[0:1]
	s_mov_b32 s0, -1
	s_barrier
	s_nop 0
	v_mbcnt_lo_u32_b32 v0, s0, 0
	v_mbcnt_hi_u32_b32 v0, s0, v0
	v_or_b32_e32 v6, s33, v0
	v_readlane_b32 s0, v254, 3
	s_nop 1
	v_lshl_add_u32 v0, s0, 9, v6
	v_ashrrev_i32_e32 v0, 6, v0
	s_mov_b32 s0, 0xc000
	v_cmp_gt_i32_e32 vcc, s0, v0
	s_and_saveexec_b64 s[0:1], vcc
	s_cbranch_execz .LBB0_661
	v_readlane_b32 s2, v254, 0
	v_readlane_b32 s3, v254, 1
	s_load_dwordx4 s[4:7], s[2:3], 0xa8
	s_load_dwordx2 s[0:1], s[2:3], 0xc8
	v_lshlrev_b32_e32 v1, 2, v6
	v_and_b32_e32 v1, 0xfc, v1
	v_lshlrev_b32_e32 v4, 1, v1
	v_mov_b32_e32 v5, 0
	v_mbcnt_hi_u32_b32 v7, -1, v148
	s_waitcnt lgkmcnt(0)
	v_lshl_add_u64 v[2:3], s[0:1], 0, v[4:5]
	v_and_b32_e32 v4, 64, v7
	v_add_u32_e32 v13, 64, v4
	v_lshlrev_b32_e32 v4, 2, v1
	v_xor_b32_e32 v1, 1, v7
	v_cmp_lt_i32_e32 vcc, v1, v13
	s_ashr_i32 s39, s38, 31
	v_lshl_add_u64 v[4:5], s[4:5], 0, v[4:5]
	v_cndmask_b32_e32 v1, v7, v1, vcc
	v_lshlrev_b32_e32 v8, 2, v1
	v_xor_b32_e32 v1, 2, v7
	v_cmp_lt_i32_e32 vcc, v1, v13
	s_lshl_b64 s[0:1], s[38:39], 12
	s_mov_b64 s[2:3], 0
	v_cndmask_b32_e32 v1, v7, v1, vcc
	v_lshlrev_b32_e32 v9, 2, v1
	v_xor_b32_e32 v1, 4, v7
	v_cmp_lt_i32_e32 vcc, v1, v13
	s_mov_b32 s8, 0xbfff
	s_nop 0
	v_cndmask_b32_e32 v1, v7, v1, vcc
	v_lshlrev_b32_e32 v10, 2, v1
	v_xor_b32_e32 v1, 8, v7
	v_cmp_lt_i32_e32 vcc, v1, v13
	s_nop 1
	v_cndmask_b32_e32 v1, v7, v1, vcc
	v_lshlrev_b32_e32 v11, 2, v1
	v_xor_b32_e32 v1, 16, v7
	v_cmp_lt_i32_e32 vcc, v1, v13
	s_nop 1
	v_cndmask_b32_e32 v1, v7, v1, vcc
	v_lshlrev_b32_e32 v12, 2, v1
	v_xor_b32_e32 v1, 32, v7
	v_cmp_lt_i32_e32 vcc, v1, v13
	s_nop 1
	v_cndmask_b32_e32 v1, v7, v1, vcc
	v_lshlrev_b32_e32 v13, 2, v1
	v_ashrrev_i32_e32 v1, 31, v0
	v_lshlrev_b64 v[14:15], 12, v[0:1]
	v_and_b32_e32 v1, 63, v6
	v_lshl_or_b32 v14, v1, 4, v14
	v_lshl_add_u64 v[6:7], s[6:7], 0, v[14:15]
	s_movk_i32 s6, 0x3fff
	v_mov_b32_e32 v1, 0x358637bd
	s_mov_b32 s7, 0x800000
	global_load_dwordx4 v[200:203], v[4:5], off
	global_load_dwordx4 v[204:207], v[4:5], off offset:1024
	global_load_dwordx4 v[208:211], v[4:5], off offset:2048
	global_load_dwordx4 v[212:215], v[4:5], off offset:3072
	s_waitcnt vmcnt(0)
	s_branch .LBB0_657
.LBB0_656:
	s_or_b64 exec, exec, s[4:5]
	v_and_b32_e32 v16, v16, v0
	v_add3_u32 v14, v16, v15, v14
	v_ashrrev_i32_e32 v15, 31, v14
	v_lshlrev_b64 v[14:15], 11, v[14:15]
	v_lshl_add_u64 v[18:19], v[2:3], 0, v[14:15]
	global_load_dwordx2 v[20:21], v[18:19], off
	global_load_dwordx2 v[22:23], v[18:19], off offset:512
	global_load_dwordx2 v[24:25], v[18:19], off offset:1024
	global_load_dwordx2 v[26:27], v[18:19], off offset:1536
	v_add_u32_e32 v0, s38, v0
	s_waitcnt vmcnt(3)
	v_and_b32_e32 v19, 0xffff0000, v20
	v_and_b32_e32 v29, 0xffff0000, v21
	v_lshlrev_b32_e32 v28, 16, v21
	s_waitcnt vmcnt(2)
	v_and_b32_e32 v21, 0xffff0000, v22
	v_lshlrev_b32_e32 v18, 16, v20
	v_lshlrev_b32_e32 v20, 16, v22
	v_and_b32_e32 v31, 0xffff0000, v23
	v_lshlrev_b32_e32 v30, 16, v23
	s_waitcnt vmcnt(1)
	v_and_b32_e32 v23, 0xffff0000, v24
	v_and_b32_e32 v33, 0xffff0000, v25
	v_lshlrev_b32_e32 v32, 16, v25
	s_waitcnt vmcnt(0)
	v_and_b32_e32 v25, 0xffff0000, v26
	v_mov_b32_e32 v36, v19
	v_mov_b32_e32 v37, v21
	v_lshlrev_b32_e32 v22, 16, v24
	v_lshlrev_b32_e32 v24, 16, v26
	v_and_b32_e32 v35, 0xffff0000, v27
	v_lshlrev_b32_e32 v34, 16, v27
	v_mov_b32_e32 v26, v18
	v_mov_b32_e32 v27, v20
	v_mov_b32_e32 v44, v23
	v_mov_b32_e32 v45, v25
	v_pk_mul_f32 v[36:37], v[36:37], v[36:37]
	v_mov_b32_e32 v38, v28
	v_mov_b32_e32 v39, v30
	v_mov_b32_e32 v42, v22
	v_mov_b32_e32 v43, v24
	v_pk_mul_f32 v[44:45], v[44:45], v[44:45]
	v_pk_fma_f32 v[26:27], v[26:27], v[26:27], v[36:37]
	v_mov_b32_e32 v40, v29
	v_mov_b32_e32 v41, v31
	v_mov_b32_e32 v46, v32
	v_mov_b32_e32 v47, v34
	v_pk_fma_f32 v[36:37], v[42:43], v[42:43], v[44:45]
	v_pk_fma_f32 v[26:27], v[38:39], v[38:39], v[26:27]
	v_mov_b32_e32 v48, v33
	v_mov_b32_e32 v49, v35
	v_pk_fma_f32 v[36:37], v[46:47], v[46:47], v[36:37]
	v_pk_fma_f32 v[26:27], v[40:41], v[40:41], v[26:27]
	v_pk_fma_f32 v[36:37], v[48:49], v[48:49], v[36:37]
	v_add_f32_e32 v26, v26, v27
	v_add_f32_e32 v26, v26, v36
	v_add_f32_e32 v26, v26, v37
	ds_bpermute_b32 v27, v8, v26
	s_waitcnt lgkmcnt(0)
	v_add_f32_e32 v26, v26, v27
	ds_bpermute_b32 v27, v9, v26
	s_waitcnt lgkmcnt(0)
	v_add_f32_e32 v26, v26, v27
	ds_bpermute_b32 v27, v10, v26
	s_waitcnt lgkmcnt(0)
	v_add_f32_e32 v26, v26, v27
	ds_bpermute_b32 v27, v11, v26
	s_waitcnt lgkmcnt(0)
	v_add_f32_e32 v26, v26, v27
	ds_bpermute_b32 v27, v12, v26
	s_waitcnt lgkmcnt(0)
	v_add_f32_e32 v26, v26, v27
	ds_bpermute_b32 v27, v13, v26
	s_waitcnt lgkmcnt(0)
	v_add_f32_e32 v26, v26, v27
	v_fmamk_f32 v26, v26, 0x3a800000, v1
	v_mul_f32_e32 v27, 0x4b800000, v26
	v_cmp_gt_f32_e32 vcc, s7, v26
	s_nop 1
	v_cndmask_b32_e32 v26, v26, v27, vcc
	v_rsq_f32_e32 v26, v26
	s_nop 0
	v_mul_f32_e32 v27, 0x45800000, v26
	v_cndmask_b32_e32 v26, v26, v27, vcc
	v_pk_mul_f32 v[18:19], v[26:27], v[18:19] op_sel_hi:[0,1]
	v_pk_mul_f32 v[28:29], v[26:27], v[28:29] op_sel_hi:[0,1]
	s_nop 0
	v_mov_b64_e32 v[14:15], v[200:201]
	v_mov_b64_e32 v[16:17], v[202:203]
	v_pk_mul_f32 v[14:15], v[14:15], v[18:19]
	v_pk_mul_f32 v[16:17], v[16:17], v[28:29]
	global_store_dwordx4 v[6:7], v[14:17], off
	v_pk_mul_f32 v[18:19], v[26:27], v[20:21] op_sel_hi:[0,1]
	v_pk_mul_f32 v[20:21], v[26:27], v[30:31] op_sel_hi:[0,1]
	v_cmp_lt_i32_e32 vcc, s8, v0
	s_or_b64 s[2:3], vcc, s[2:3]
	s_nop 0
	v_mov_b64_e32 v[14:15], v[204:205]
	v_mov_b64_e32 v[16:17], v[206:207]
	v_pk_mul_f32 v[14:15], v[14:15], v[18:19]
	v_pk_mul_f32 v[16:17], v[16:17], v[20:21]
	global_store_dwordx4 v[6:7], v[14:17], off offset:1024
	v_pk_mul_f32 v[18:19], v[26:27], v[22:23] op_sel_hi:[0,1]
	v_pk_mul_f32 v[20:21], v[26:27], v[32:33] op_sel_hi:[0,1]
	s_nop 0
	v_mov_b64_e32 v[14:15], v[208:209]
	v_mov_b64_e32 v[16:17], v[210:211]
	v_pk_mul_f32 v[14:15], v[14:15], v[18:19]
	v_pk_mul_f32 v[16:17], v[20:21], v[16:17]
	global_store_dwordx4 v[6:7], v[14:17], off offset:2048
	v_pk_mul_f32 v[18:19], v[26:27], v[24:25] op_sel_hi:[0,1]
	v_pk_mul_f32 v[20:21], v[26:27], v[34:35] op_sel_hi:[0,1]
	s_nop 0
	v_mov_b64_e32 v[14:15], v[212:213]
	v_mov_b64_e32 v[16:17], v[214:215]
	v_pk_mul_f32 v[14:15], v[18:19], v[14:15]
	v_pk_mul_f32 v[16:17], v[20:21], v[16:17]
	global_store_dwordx4 v[6:7], v[14:17], off offset:3072
	v_lshl_add_u64 v[6:7], v[6:7], 0, s[0:1]
	s_andn2_b64 exec, exec, s[2:3]
	s_cbranch_execz .LBB0_661
